# c8 plus hand-written RG in-projection epilogue: packed-f32 gelu_tanh (same formula, fused constants), SGPR base stepped per row group
# baseline (speedup 1.0000x reference)
; __device__ __forceinline__ unsigned pk2(float lo, float hi) { f32x2 v = {lo, hi}; bf16x2_t b = __builtin_convertvector(v, bf16x2_t); return __builtin_bit_cast(unsigned, b); }
; __device__ __forceinline__ float gelu_tanh_(float v) { const float u = 1.5957691216057308f * (v + 0.044715f * v * v * v); return v * frcp_(1.0f + __expf(-u)); }
;     __device__ __forceinline__ void operator()(const AccT& acc, const Unit& u, int wr, int wc, int fr_in, int fq_in) const {
;         int fr = fr_in, fq = fq_in; asm volatile("" : "+v"(fr), "+v"(fq));
;         const bool isg = u.pn < 8; bf16* base = isg ? GATE : URAW;
;         const int row0 = u.pm * BM + wr * 64 + fr, col0 = (u.pn & 7) * BM + wc * 32 + 8 * fq;
; #pragma unroll
;         for (int ai = 0; ai < 2; ++ai)
; #pragma unroll
;             for (int m = 0; m < 4; ++m) { bf16* rowp = base + (size_t)(row0 + ai * HALF + m * 16) * D + col0;
; #pragma unroll
;                 for (int bj = 0; bj < 2; ++bj) { f32x4 v0 = acc[ai][bj][m][0], v1 = acc[ai][bj][m][1];
;                     if (isg) {
; #pragma unroll
;                         for (int j = 0; j < 4; ++j) { v0[j] = gelu_tanh_(v0[j]); v1[j] = gelu_tanh_(v1[j]); } }
;                     u32x4 w; w.x = pk2(v0[0], v0[1]); w.y = pk2(v0[2], v0[3]); w.z = pk2(v1[0], v1[1]); w.w = pk2(v1[2], v1[3]);
;                     *(u32x4*)(rowp + bj * HALF) = w; } }
;     }
.LBB0_742:
	s_lshl_b32 s22, s55, 8
	s_add_i32 s22, s22, s47
	s_lshl_b32 s22, s22, 12
	s_and_b32 s23, s54, 7
	s_lshl_b32 s23, s23, 9
	s_add_i32 s22, s22, s23
	s_lshl_b32 s23, s48, 1
	s_add_i32 s22, s22, s23
	v_lshlrev_b32_e32 v134, 12, v1
	v_lshl_add_u32 v134, v140, 4, v134
	s_cmp_lt_i32 s54, 8
	s_cselect_b32 s0, s52, s12
	s_cselect_b32 s1, s53, s13
	s_cselect_b64 s[40:41], 0, -1
	s_mov_b64 vcc, s[40:41]
	s_add_u32 s0, s0, s22
	s_addc_u32 s1, s1, 0
	s_movk_i32 s64, 0x4000
	s_mov_b32 s33, 0x18000
	s_mov_b32 s35, 0xa000
	s_mov_b32 s34, 0x1c000
	s_cbranch_vccnz .Lrgepi_raw
	v_mov_b32_e32 v144, 0xbdd2d3e8
	v_mov_b32_e32 v146, 0xc0135761
	v_pk_mul_f32 v[136:137], v[126:127], v[126:127]
	v_pk_mul_f32 v[138:139], v[128:129], v[128:129]
	v_pk_fma_f32 v[136:137], v[136:137], v[144:145], v[146:147] op_sel_hi:[1,0,0]
	v_pk_fma_f32 v[138:139], v[138:139], v[144:145], v[146:147] op_sel_hi:[1,0,0]
	v_pk_mul_f32 v[136:137], v[126:127], v[136:137]
	v_pk_mul_f32 v[138:139], v[128:129], v[138:139]
	v_exp_f32_e32 v136, v136
	v_exp_f32_e32 v137, v137
	v_exp_f32_e32 v138, v138
	v_exp_f32_e32 v139, v139
	v_pk_add_f32 v[136:137], v[136:137], 1.0 op_sel_hi:[1,0]
	v_pk_add_f32 v[138:139], v[138:139], 1.0 op_sel_hi:[1,0]
	v_rcp_f32_e32 v136, v136
	v_rcp_f32_e32 v137, v137
	v_rcp_f32_e32 v138, v138
	v_rcp_f32_e32 v139, v139
	v_pk_mul_f32 v[126:127], v[126:127], v[136:137]
	v_pk_mul_f32 v[128:129], v[128:129], v[138:139]
	v_pk_mul_f32 v[136:137], v[122:123], v[122:123]
	v_pk_mul_f32 v[138:139], v[124:125], v[124:125]
	v_pk_fma_f32 v[136:137], v[136:137], v[144:145], v[146:147] op_sel_hi:[1,0,0]
	v_pk_fma_f32 v[138:139], v[138:139], v[144:145], v[146:147] op_sel_hi:[1,0,0]
	v_pk_mul_f32 v[136:137], v[122:123], v[136:137]
	v_pk_mul_f32 v[138:139], v[124:125], v[138:139]
	v_exp_f32_e32 v136, v136
	v_exp_f32_e32 v137, v137
	v_exp_f32_e32 v138, v138
	v_exp_f32_e32 v139, v139
	v_pk_add_f32 v[136:137], v[136:137], 1.0 op_sel_hi:[1,0]
	v_pk_add_f32 v[138:139], v[138:139], 1.0 op_sel_hi:[1,0]
	v_rcp_f32_e32 v136, v136
	v_rcp_f32_e32 v137, v137
	v_rcp_f32_e32 v138, v138
	v_rcp_f32_e32 v139, v139
	v_pk_mul_f32 v[122:123], v[122:123], v[136:137]
	v_pk_mul_f32 v[124:125], v[124:125], v[138:139]
	v_cvt_pk_bf16_f32 v126, v126, v127
	v_cvt_pk_bf16_f32 v127, v128, v129
	v_cvt_pk_bf16_f32 v128, v122, v123
	v_cvt_pk_bf16_f32 v129, v124, v125
	global_store_dwordx4 v134, v[126:129], s[0:1]
	v_pk_mul_f32 v[136:137], v[118:119], v[118:119]
	v_pk_mul_f32 v[138:139], v[120:121], v[120:121]
	v_pk_fma_f32 v[136:137], v[136:137], v[144:145], v[146:147] op_sel_hi:[1,0,0]
	v_pk_fma_f32 v[138:139], v[138:139], v[144:145], v[146:147] op_sel_hi:[1,0,0]
	v_pk_mul_f32 v[136:137], v[118:119], v[136:137]
	v_pk_mul_f32 v[138:139], v[120:121], v[138:139]
	v_exp_f32_e32 v136, v136
	v_exp_f32_e32 v137, v137
	v_exp_f32_e32 v138, v138
	v_exp_f32_e32 v139, v139
	v_pk_add_f32 v[136:137], v[136:137], 1.0 op_sel_hi:[1,0]
	v_pk_add_f32 v[138:139], v[138:139], 1.0 op_sel_hi:[1,0]
	v_rcp_f32_e32 v136, v136
	v_rcp_f32_e32 v137, v137
	v_rcp_f32_e32 v138, v138
	v_rcp_f32_e32 v139, v139
	v_pk_mul_f32 v[118:119], v[118:119], v[136:137]
	v_pk_mul_f32 v[120:121], v[120:121], v[138:139]
	v_pk_mul_f32 v[136:137], v[114:115], v[114:115]
	v_pk_mul_f32 v[138:139], v[116:117], v[116:117]
	v_pk_fma_f32 v[136:137], v[136:137], v[144:145], v[146:147] op_sel_hi:[1,0,0]
	v_pk_fma_f32 v[138:139], v[138:139], v[144:145], v[146:147] op_sel_hi:[1,0,0]
	v_pk_mul_f32 v[136:137], v[114:115], v[136:137]
	v_pk_mul_f32 v[138:139], v[116:117], v[138:139]
	v_exp_f32_e32 v136, v136
	v_exp_f32_e32 v137, v137
	v_exp_f32_e32 v138, v138
	v_exp_f32_e32 v139, v139
	v_pk_add_f32 v[136:137], v[136:137], 1.0 op_sel_hi:[1,0]
	v_pk_add_f32 v[138:139], v[138:139], 1.0 op_sel_hi:[1,0]
	v_rcp_f32_e32 v136, v136
	v_rcp_f32_e32 v137, v137
	v_rcp_f32_e32 v138, v138
	v_rcp_f32_e32 v139, v139
	v_pk_mul_f32 v[114:115], v[114:115], v[136:137]
	v_pk_mul_f32 v[116:117], v[116:117], v[138:139]
	v_cvt_pk_bf16_f32 v118, v118, v119
	v_cvt_pk_bf16_f32 v119, v120, v121
	v_cvt_pk_bf16_f32 v120, v114, v115
	v_cvt_pk_bf16_f32 v121, v116, v117
	global_store_dwordx4 v134, v[118:121], s[0:1] offset:256
	s_add_u32 s0, s0, 0x10000
	s_addc_u32 s1, s1, 0
	v_pk_mul_f32 v[136:137], v[110:111], v[110:111]
	v_pk_mul_f32 v[138:139], v[112:113], v[112:113]
	v_pk_fma_f32 v[136:137], v[136:137], v[144:145], v[146:147] op_sel_hi:[1,0,0]
	v_pk_fma_f32 v[138:139], v[138:139], v[144:145], v[146:147] op_sel_hi:[1,0,0]
	v_pk_mul_f32 v[136:137], v[110:111], v[136:137]
	v_pk_mul_f32 v[138:139], v[112:113], v[138:139]
	v_exp_f32_e32 v136, v136
	v_exp_f32_e32 v137, v137
	v_exp_f32_e32 v138, v138
	v_exp_f32_e32 v139, v139
	v_pk_add_f32 v[136:137], v[136:137], 1.0 op_sel_hi:[1,0]
	v_pk_add_f32 v[138:139], v[138:139], 1.0 op_sel_hi:[1,0]
	v_rcp_f32_e32 v136, v136
	v_rcp_f32_e32 v137, v137
	v_rcp_f32_e32 v138, v138
	v_rcp_f32_e32 v139, v139
	v_pk_mul_f32 v[110:111], v[110:111], v[136:137]
	v_pk_mul_f32 v[112:113], v[112:113], v[138:139]
	v_pk_mul_f32 v[136:137], v[106:107], v[106:107]
	v_pk_mul_f32 v[138:139], v[108:109], v[108:109]
	v_pk_fma_f32 v[136:137], v[136:137], v[144:145], v[146:147] op_sel_hi:[1,0,0]
	v_pk_fma_f32 v[138:139], v[138:139], v[144:145], v[146:147] op_sel_hi:[1,0,0]
	v_pk_mul_f32 v[136:137], v[106:107], v[136:137]
	v_pk_mul_f32 v[138:139], v[108:109], v[138:139]
	v_exp_f32_e32 v136, v136
	v_exp_f32_e32 v137, v137
	v_exp_f32_e32 v138, v138
	v_exp_f32_e32 v139, v139
	v_pk_add_f32 v[136:137], v[136:137], 1.0 op_sel_hi:[1,0]
	v_pk_add_f32 v[138:139], v[138:139], 1.0 op_sel_hi:[1,0]
	v_rcp_f32_e32 v136, v136
	v_rcp_f32_e32 v137, v137
	v_rcp_f32_e32 v138, v138
	v_rcp_f32_e32 v139, v139
; __device__ __forceinline__ unsigned pk2(float lo, float hi) { f32x2 v = {lo, hi}; bf16x2_t b = __builtin_convertvector(v, bf16x2_t); return __builtin_bit_cast(unsigned, b); }
; __device__ __forceinline__ float gelu_tanh_(float v) { const float u = 1.5957691216057308f * (v + 0.044715f * v * v * v); return v * frcp_(1.0f + __expf(-u)); }
;     __device__ __forceinline__ void operator()(const AccT& acc, const Unit& u, int wr, int wc, int fr_in, int fq_in) const {
;     ...
;             for (int m = 0; m < 4; ++m) { bf16* rowp = base + (size_t)(row0 + ai * HALF + m * 16) * D + col0;
; #pragma unroll
;                 for (int bj = 0; bj < 2; ++bj) { f32x4 v0 = acc[ai][bj][m][0], v1 = acc[ai][bj][m][1];
;                     if (isg) {
; #pragma unroll
;                         for (int j = 0; j < 4; ++j) { v0[j] = gelu_tanh_(v0[j]); v1[j] = gelu_tanh_(v1[j]); } }
;                     u32x4 w; w.x = pk2(v0[0], v0[1]); w.y = pk2(v0[2], v0[3]); w.z = pk2(v1[0], v1[1]); w.w = pk2(v1[2], v1[3]);
;                     *(u32x4*)(rowp + bj * HALF) = w; } }
	v_pk_mul_f32 v[106:107], v[106:107], v[136:137]
	v_pk_mul_f32 v[108:109], v[108:109], v[138:139]
	v_cvt_pk_bf16_f32 v110, v110, v111
	v_cvt_pk_bf16_f32 v111, v112, v113
	v_cvt_pk_bf16_f32 v112, v106, v107
	v_cvt_pk_bf16_f32 v113, v108, v109
	global_store_dwordx4 v134, v[110:113], s[0:1]
	v_pk_mul_f32 v[136:137], v[102:103], v[102:103]
	v_pk_mul_f32 v[138:139], v[104:105], v[104:105]
	v_pk_fma_f32 v[136:137], v[136:137], v[144:145], v[146:147] op_sel_hi:[1,0,0]
	v_pk_fma_f32 v[138:139], v[138:139], v[144:145], v[146:147] op_sel_hi:[1,0,0]
	v_pk_mul_f32 v[136:137], v[102:103], v[136:137]
	v_pk_mul_f32 v[138:139], v[104:105], v[138:139]
	v_exp_f32_e32 v136, v136
	v_exp_f32_e32 v137, v137
	v_exp_f32_e32 v138, v138
	v_exp_f32_e32 v139, v139
	v_pk_add_f32 v[136:137], v[136:137], 1.0 op_sel_hi:[1,0]
	v_pk_add_f32 v[138:139], v[138:139], 1.0 op_sel_hi:[1,0]
	v_rcp_f32_e32 v136, v136
	v_rcp_f32_e32 v137, v137
	v_rcp_f32_e32 v138, v138
	v_rcp_f32_e32 v139, v139
	v_pk_mul_f32 v[102:103], v[102:103], v[136:137]
	v_pk_mul_f32 v[104:105], v[104:105], v[138:139]
	v_pk_mul_f32 v[136:137], v[98:99], v[98:99]
	v_pk_mul_f32 v[138:139], v[100:101], v[100:101]
	v_pk_fma_f32 v[136:137], v[136:137], v[144:145], v[146:147] op_sel_hi:[1,0,0]
	v_pk_fma_f32 v[138:139], v[138:139], v[144:145], v[146:147] op_sel_hi:[1,0,0]
	v_pk_mul_f32 v[136:137], v[98:99], v[136:137]
	v_pk_mul_f32 v[138:139], v[100:101], v[138:139]
	v_exp_f32_e32 v136, v136
	v_exp_f32_e32 v137, v137
	v_exp_f32_e32 v138, v138
	v_exp_f32_e32 v139, v139
	v_pk_add_f32 v[136:137], v[136:137], 1.0 op_sel_hi:[1,0]
	v_pk_add_f32 v[138:139], v[138:139], 1.0 op_sel_hi:[1,0]
	v_rcp_f32_e32 v136, v136
	v_rcp_f32_e32 v137, v137
	v_rcp_f32_e32 v138, v138
	v_rcp_f32_e32 v139, v139
	v_pk_mul_f32 v[98:99], v[98:99], v[136:137]
	v_pk_mul_f32 v[100:101], v[100:101], v[138:139]
	v_cvt_pk_bf16_f32 v102, v102, v103
	v_cvt_pk_bf16_f32 v103, v104, v105
	v_cvt_pk_bf16_f32 v104, v98, v99
	v_cvt_pk_bf16_f32 v105, v100, v101
	global_store_dwordx4 v134, v[102:105], s[0:1] offset:256
	s_add_u32 s0, s0, 0x10000
	s_addc_u32 s1, s1, 0
	v_pk_mul_f32 v[136:137], v[94:95], v[94:95]
	v_pk_mul_f32 v[138:139], v[96:97], v[96:97]
	v_pk_fma_f32 v[136:137], v[136:137], v[144:145], v[146:147] op_sel_hi:[1,0,0]
	v_pk_fma_f32 v[138:139], v[138:139], v[144:145], v[146:147] op_sel_hi:[1,0,0]
	v_pk_mul_f32 v[136:137], v[94:95], v[136:137]
	v_pk_mul_f32 v[138:139], v[96:97], v[138:139]
	v_exp_f32_e32 v136, v136
	v_exp_f32_e32 v137, v137
	v_exp_f32_e32 v138, v138
	v_exp_f32_e32 v139, v139
	v_pk_add_f32 v[136:137], v[136:137], 1.0 op_sel_hi:[1,0]
	v_pk_add_f32 v[138:139], v[138:139], 1.0 op_sel_hi:[1,0]
	v_rcp_f32_e32 v136, v136
	v_rcp_f32_e32 v137, v137
	v_rcp_f32_e32 v138, v138
	v_rcp_f32_e32 v139, v139
	v_pk_mul_f32 v[94:95], v[94:95], v[136:137]
	v_pk_mul_f32 v[96:97], v[96:97], v[138:139]
	v_pk_mul_f32 v[136:137], v[90:91], v[90:91]
	v_pk_mul_f32 v[138:139], v[92:93], v[92:93]
	v_pk_fma_f32 v[136:137], v[136:137], v[144:145], v[146:147] op_sel_hi:[1,0,0]
	v_pk_fma_f32 v[138:139], v[138:139], v[144:145], v[146:147] op_sel_hi:[1,0,0]
	v_pk_mul_f32 v[136:137], v[90:91], v[136:137]
	v_pk_mul_f32 v[138:139], v[92:93], v[138:139]
	v_exp_f32_e32 v136, v136
	v_exp_f32_e32 v137, v137
	v_exp_f32_e32 v138, v138
	v_exp_f32_e32 v139, v139
	v_pk_add_f32 v[136:137], v[136:137], 1.0 op_sel_hi:[1,0]
	v_pk_add_f32 v[138:139], v[138:139], 1.0 op_sel_hi:[1,0]
	v_rcp_f32_e32 v136, v136
	v_rcp_f32_e32 v137, v137
	v_rcp_f32_e32 v138, v138
	v_rcp_f32_e32 v139, v139
	v_pk_mul_f32 v[90:91], v[90:91], v[136:137]
	v_pk_mul_f32 v[92:93], v[92:93], v[138:139]
	v_cvt_pk_bf16_f32 v94, v94, v95
	v_cvt_pk_bf16_f32 v95, v96, v97
	v_cvt_pk_bf16_f32 v96, v90, v91
	v_cvt_pk_bf16_f32 v97, v92, v93
	global_store_dwordx4 v134, v[94:97], s[0:1]
	v_pk_mul_f32 v[136:137], v[86:87], v[86:87]
	v_pk_mul_f32 v[138:139], v[88:89], v[88:89]
	v_pk_fma_f32 v[136:137], v[136:137], v[144:145], v[146:147] op_sel_hi:[1,0,0]
	v_pk_fma_f32 v[138:139], v[138:139], v[144:145], v[146:147] op_sel_hi:[1,0,0]
	v_pk_mul_f32 v[136:137], v[86:87], v[136:137]
	v_pk_mul_f32 v[138:139], v[88:89], v[138:139]
	v_exp_f32_e32 v136, v136
	v_exp_f32_e32 v137, v137
	v_exp_f32_e32 v138, v138
	v_exp_f32_e32 v139, v139
	v_pk_add_f32 v[136:137], v[136:137], 1.0 op_sel_hi:[1,0]
	v_pk_add_f32 v[138:139], v[138:139], 1.0 op_sel_hi:[1,0]
	v_rcp_f32_e32 v136, v136
	v_rcp_f32_e32 v137, v137
	v_rcp_f32_e32 v138, v138
	v_rcp_f32_e32 v139, v139
	v_pk_mul_f32 v[86:87], v[86:87], v[136:137]
	v_pk_mul_f32 v[88:89], v[88:89], v[138:139]
	v_pk_mul_f32 v[136:137], v[82:83], v[82:83]
	v_pk_mul_f32 v[138:139], v[84:85], v[84:85]
	v_pk_fma_f32 v[136:137], v[136:137], v[144:145], v[146:147] op_sel_hi:[1,0,0]
	v_pk_fma_f32 v[138:139], v[138:139], v[144:145], v[146:147] op_sel_hi:[1,0,0]
	v_pk_mul_f32 v[136:137], v[82:83], v[136:137]
	v_pk_mul_f32 v[138:139], v[84:85], v[138:139]
	v_exp_f32_e32 v136, v136
	v_exp_f32_e32 v137, v137
	v_exp_f32_e32 v138, v138
	v_exp_f32_e32 v139, v139
	v_pk_add_f32 v[136:137], v[136:137], 1.0 op_sel_hi:[1,0]
	v_pk_add_f32 v[138:139], v[138:139], 1.0 op_sel_hi:[1,0]
	v_rcp_f32_e32 v136, v136
	v_rcp_f32_e32 v137, v137
	v_rcp_f32_e32 v138, v138
	v_rcp_f32_e32 v139, v139
	v_pk_mul_f32 v[82:83], v[82:83], v[136:137]
	v_pk_mul_f32 v[84:85], v[84:85], v[138:139]
	v_cvt_pk_bf16_f32 v86, v86, v87
	v_cvt_pk_bf16_f32 v87, v88, v89
	v_cvt_pk_bf16_f32 v88, v82, v83
	v_cvt_pk_bf16_f32 v89, v84, v85
	global_store_dwordx4 v134, v[86:89], s[0:1] offset:256
	s_add_u32 s0, s0, 0x10000
	s_addc_u32 s1, s1, 0
	v_pk_mul_f32 v[136:137], v[78:79], v[78:79]
	v_pk_mul_f32 v[138:139], v[80:81], v[80:81]
; __device__ __forceinline__ unsigned pk2(float lo, float hi) { f32x2 v = {lo, hi}; bf16x2_t b = __builtin_convertvector(v, bf16x2_t); return __builtin_bit_cast(unsigned, b); }
; __device__ __forceinline__ float gelu_tanh_(float v) { const float u = 1.5957691216057308f * (v + 0.044715f * v * v * v); return v * frcp_(1.0f + __expf(-u)); }
;     __device__ __forceinline__ void operator()(const AccT& acc, const Unit& u, int wr, int wc, int fr_in, int fq_in) const {
;     ...
;             for (int m = 0; m < 4; ++m) { bf16* rowp = base + (size_t)(row0 + ai * HALF + m * 16) * D + col0;
; #pragma unroll
;                 for (int bj = 0; bj < 2; ++bj) { f32x4 v0 = acc[ai][bj][m][0], v1 = acc[ai][bj][m][1];
;                     if (isg) {
; #pragma unroll
;                         for (int j = 0; j < 4; ++j) { v0[j] = gelu_tanh_(v0[j]); v1[j] = gelu_tanh_(v1[j]); } }
;                     u32x4 w; w.x = pk2(v0[0], v0[1]); w.y = pk2(v0[2], v0[3]); w.z = pk2(v1[0], v1[1]); w.w = pk2(v1[2], v1[3]);
;                     *(u32x4*)(rowp + bj * HALF) = w; } }
	v_pk_fma_f32 v[136:137], v[136:137], v[144:145], v[146:147] op_sel_hi:[1,0,0]
	v_pk_fma_f32 v[138:139], v[138:139], v[144:145], v[146:147] op_sel_hi:[1,0,0]
	v_pk_mul_f32 v[136:137], v[78:79], v[136:137]
	v_pk_mul_f32 v[138:139], v[80:81], v[138:139]
	v_exp_f32_e32 v136, v136
	v_exp_f32_e32 v137, v137
	v_exp_f32_e32 v138, v138
	v_exp_f32_e32 v139, v139
	v_pk_add_f32 v[136:137], v[136:137], 1.0 op_sel_hi:[1,0]
	v_pk_add_f32 v[138:139], v[138:139], 1.0 op_sel_hi:[1,0]
	v_rcp_f32_e32 v136, v136
	v_rcp_f32_e32 v137, v137
	v_rcp_f32_e32 v138, v138
	v_rcp_f32_e32 v139, v139
	v_pk_mul_f32 v[78:79], v[78:79], v[136:137]
	v_pk_mul_f32 v[80:81], v[80:81], v[138:139]
	v_pk_mul_f32 v[136:137], v[74:75], v[74:75]
	v_pk_mul_f32 v[138:139], v[76:77], v[76:77]
	v_pk_fma_f32 v[136:137], v[136:137], v[144:145], v[146:147] op_sel_hi:[1,0,0]
	v_pk_fma_f32 v[138:139], v[138:139], v[144:145], v[146:147] op_sel_hi:[1,0,0]
	v_pk_mul_f32 v[136:137], v[74:75], v[136:137]
	v_pk_mul_f32 v[138:139], v[76:77], v[138:139]
	v_exp_f32_e32 v136, v136
	v_exp_f32_e32 v137, v137
	v_exp_f32_e32 v138, v138
	v_exp_f32_e32 v139, v139
	v_pk_add_f32 v[136:137], v[136:137], 1.0 op_sel_hi:[1,0]
	v_pk_add_f32 v[138:139], v[138:139], 1.0 op_sel_hi:[1,0]
	v_rcp_f32_e32 v136, v136
	v_rcp_f32_e32 v137, v137
	v_rcp_f32_e32 v138, v138
	v_rcp_f32_e32 v139, v139
	v_pk_mul_f32 v[74:75], v[74:75], v[136:137]
	v_pk_mul_f32 v[76:77], v[76:77], v[138:139]
	v_cvt_pk_bf16_f32 v78, v78, v79
	v_cvt_pk_bf16_f32 v79, v80, v81
	v_cvt_pk_bf16_f32 v80, v74, v75
	v_cvt_pk_bf16_f32 v81, v76, v77
	global_store_dwordx4 v134, v[78:81], s[0:1]
	v_pk_mul_f32 v[136:137], v[70:71], v[70:71]
	v_pk_mul_f32 v[138:139], v[72:73], v[72:73]
	v_pk_fma_f32 v[136:137], v[136:137], v[144:145], v[146:147] op_sel_hi:[1,0,0]
	v_pk_fma_f32 v[138:139], v[138:139], v[144:145], v[146:147] op_sel_hi:[1,0,0]
	v_pk_mul_f32 v[136:137], v[70:71], v[136:137]
	v_pk_mul_f32 v[138:139], v[72:73], v[138:139]
	v_exp_f32_e32 v136, v136
	v_exp_f32_e32 v137, v137
	v_exp_f32_e32 v138, v138
	v_exp_f32_e32 v139, v139
	v_pk_add_f32 v[136:137], v[136:137], 1.0 op_sel_hi:[1,0]
	v_pk_add_f32 v[138:139], v[138:139], 1.0 op_sel_hi:[1,0]
	v_rcp_f32_e32 v136, v136
	v_rcp_f32_e32 v137, v137
	v_rcp_f32_e32 v138, v138
	v_rcp_f32_e32 v139, v139
	v_pk_mul_f32 v[70:71], v[70:71], v[136:137]
	v_pk_mul_f32 v[72:73], v[72:73], v[138:139]
	v_pk_mul_f32 v[136:137], v[66:67], v[66:67]
	v_pk_mul_f32 v[138:139], v[68:69], v[68:69]
	v_pk_fma_f32 v[136:137], v[136:137], v[144:145], v[146:147] op_sel_hi:[1,0,0]
	v_pk_fma_f32 v[138:139], v[138:139], v[144:145], v[146:147] op_sel_hi:[1,0,0]
	v_pk_mul_f32 v[136:137], v[66:67], v[136:137]
	v_pk_mul_f32 v[138:139], v[68:69], v[138:139]
	v_exp_f32_e32 v136, v136
	v_exp_f32_e32 v137, v137
	v_exp_f32_e32 v138, v138
	v_exp_f32_e32 v139, v139
	v_pk_add_f32 v[136:137], v[136:137], 1.0 op_sel_hi:[1,0]
	v_pk_add_f32 v[138:139], v[138:139], 1.0 op_sel_hi:[1,0]
	v_rcp_f32_e32 v136, v136
	v_rcp_f32_e32 v137, v137
	v_rcp_f32_e32 v138, v138
	v_rcp_f32_e32 v139, v139
	v_pk_mul_f32 v[66:67], v[66:67], v[136:137]
	v_pk_mul_f32 v[68:69], v[68:69], v[138:139]
	v_cvt_pk_bf16_f32 v70, v70, v71
	v_cvt_pk_bf16_f32 v71, v72, v73
	v_cvt_pk_bf16_f32 v72, v66, v67
	v_cvt_pk_bf16_f32 v73, v68, v69
	global_store_dwordx4 v134, v[70:73], s[0:1] offset:256
	s_add_u32 s0, s0, 0x50000
	s_addc_u32 s1, s1, 0
	v_pk_mul_f32 v[136:137], v[62:63], v[62:63]
	v_pk_mul_f32 v[138:139], v[64:65], v[64:65]
	v_pk_fma_f32 v[136:137], v[136:137], v[144:145], v[146:147] op_sel_hi:[1,0,0]
	v_pk_fma_f32 v[138:139], v[138:139], v[144:145], v[146:147] op_sel_hi:[1,0,0]
	v_pk_mul_f32 v[136:137], v[62:63], v[136:137]
	v_pk_mul_f32 v[138:139], v[64:65], v[138:139]
	v_exp_f32_e32 v136, v136
	v_exp_f32_e32 v137, v137
	v_exp_f32_e32 v138, v138
	v_exp_f32_e32 v139, v139
	v_pk_add_f32 v[136:137], v[136:137], 1.0 op_sel_hi:[1,0]
	v_pk_add_f32 v[138:139], v[138:139], 1.0 op_sel_hi:[1,0]
	v_rcp_f32_e32 v136, v136
	v_rcp_f32_e32 v137, v137
	v_rcp_f32_e32 v138, v138
	v_rcp_f32_e32 v139, v139
	v_pk_mul_f32 v[62:63], v[62:63], v[136:137]
	v_pk_mul_f32 v[64:65], v[64:65], v[138:139]
	v_pk_mul_f32 v[136:137], v[58:59], v[58:59]
	v_pk_mul_f32 v[138:139], v[60:61], v[60:61]
	v_pk_fma_f32 v[136:137], v[136:137], v[144:145], v[146:147] op_sel_hi:[1,0,0]
	v_pk_fma_f32 v[138:139], v[138:139], v[144:145], v[146:147] op_sel_hi:[1,0,0]
	v_pk_mul_f32 v[136:137], v[58:59], v[136:137]
	v_pk_mul_f32 v[138:139], v[60:61], v[138:139]
	v_exp_f32_e32 v136, v136
	v_exp_f32_e32 v137, v137
	v_exp_f32_e32 v138, v138
	v_exp_f32_e32 v139, v139
	v_pk_add_f32 v[136:137], v[136:137], 1.0 op_sel_hi:[1,0]
	v_pk_add_f32 v[138:139], v[138:139], 1.0 op_sel_hi:[1,0]
	v_rcp_f32_e32 v136, v136
	v_rcp_f32_e32 v137, v137
	v_rcp_f32_e32 v138, v138
	v_rcp_f32_e32 v139, v139
	v_pk_mul_f32 v[58:59], v[58:59], v[136:137]
	v_pk_mul_f32 v[60:61], v[60:61], v[138:139]
	v_cvt_pk_bf16_f32 v62, v62, v63
	v_cvt_pk_bf16_f32 v63, v64, v65
	v_cvt_pk_bf16_f32 v64, v58, v59
	v_cvt_pk_bf16_f32 v65, v60, v61
	global_store_dwordx4 v134, v[62:65], s[0:1]
	v_pk_mul_f32 v[136:137], v[54:55], v[54:55]
	v_pk_mul_f32 v[138:139], v[56:57], v[56:57]
	v_pk_fma_f32 v[136:137], v[136:137], v[144:145], v[146:147] op_sel_hi:[1,0,0]
	v_pk_fma_f32 v[138:139], v[138:139], v[144:145], v[146:147] op_sel_hi:[1,0,0]
	v_pk_mul_f32 v[136:137], v[54:55], v[136:137]
	v_pk_mul_f32 v[138:139], v[56:57], v[138:139]
	v_exp_f32_e32 v136, v136
	v_exp_f32_e32 v137, v137
	v_exp_f32_e32 v138, v138
	v_exp_f32_e32 v139, v139
	v_pk_add_f32 v[136:137], v[136:137], 1.0 op_sel_hi:[1,0]
	v_pk_add_f32 v[138:139], v[138:139], 1.0 op_sel_hi:[1,0]
	v_rcp_f32_e32 v136, v136
	v_rcp_f32_e32 v137, v137
; __device__ __forceinline__ unsigned pk2(float lo, float hi) { f32x2 v = {lo, hi}; bf16x2_t b = __builtin_convertvector(v, bf16x2_t); return __builtin_bit_cast(unsigned, b); }
; __device__ __forceinline__ float gelu_tanh_(float v) { const float u = 1.5957691216057308f * (v + 0.044715f * v * v * v); return v * frcp_(1.0f + __expf(-u)); }
;     __device__ __forceinline__ void operator()(const AccT& acc, const Unit& u, int wr, int wc, int fr_in, int fq_in) const {
;     ...
;             for (int m = 0; m < 4; ++m) { bf16* rowp = base + (size_t)(row0 + ai * HALF + m * 16) * D + col0;
; #pragma unroll
;                 for (int bj = 0; bj < 2; ++bj) { f32x4 v0 = acc[ai][bj][m][0], v1 = acc[ai][bj][m][1];
;                     if (isg) {
; #pragma unroll
;                         for (int j = 0; j < 4; ++j) { v0[j] = gelu_tanh_(v0[j]); v1[j] = gelu_tanh_(v1[j]); } }
;                     u32x4 w; w.x = pk2(v0[0], v0[1]); w.y = pk2(v0[2], v0[3]); w.z = pk2(v1[0], v1[1]); w.w = pk2(v1[2], v1[3]);
;                     *(u32x4*)(rowp + bj * HALF) = w; } }
	v_rcp_f32_e32 v138, v138
	v_rcp_f32_e32 v139, v139
	v_pk_mul_f32 v[54:55], v[54:55], v[136:137]
	v_pk_mul_f32 v[56:57], v[56:57], v[138:139]
	v_pk_mul_f32 v[136:137], v[50:51], v[50:51]
	v_pk_mul_f32 v[138:139], v[52:53], v[52:53]
	v_pk_fma_f32 v[136:137], v[136:137], v[144:145], v[146:147] op_sel_hi:[1,0,0]
	v_pk_fma_f32 v[138:139], v[138:139], v[144:145], v[146:147] op_sel_hi:[1,0,0]
	v_pk_mul_f32 v[136:137], v[50:51], v[136:137]
	v_pk_mul_f32 v[138:139], v[52:53], v[138:139]
	v_exp_f32_e32 v136, v136
	v_exp_f32_e32 v137, v137
	v_exp_f32_e32 v138, v138
	v_exp_f32_e32 v139, v139
	v_pk_add_f32 v[136:137], v[136:137], 1.0 op_sel_hi:[1,0]
	v_pk_add_f32 v[138:139], v[138:139], 1.0 op_sel_hi:[1,0]
	v_rcp_f32_e32 v136, v136
	v_rcp_f32_e32 v137, v137
	v_rcp_f32_e32 v138, v138
	v_rcp_f32_e32 v139, v139
	v_pk_mul_f32 v[50:51], v[50:51], v[136:137]
	v_pk_mul_f32 v[52:53], v[52:53], v[138:139]
	v_cvt_pk_bf16_f32 v54, v54, v55
	v_cvt_pk_bf16_f32 v55, v56, v57
	v_cvt_pk_bf16_f32 v56, v50, v51
	v_cvt_pk_bf16_f32 v57, v52, v53
	global_store_dwordx4 v134, v[54:57], s[0:1] offset:256
	s_add_u32 s0, s0, 0x10000
	s_addc_u32 s1, s1, 0
	v_pk_mul_f32 v[136:137], v[46:47], v[46:47]
	v_pk_mul_f32 v[138:139], v[48:49], v[48:49]
	v_pk_fma_f32 v[136:137], v[136:137], v[144:145], v[146:147] op_sel_hi:[1,0,0]
	v_pk_fma_f32 v[138:139], v[138:139], v[144:145], v[146:147] op_sel_hi:[1,0,0]
	v_pk_mul_f32 v[136:137], v[46:47], v[136:137]
	v_pk_mul_f32 v[138:139], v[48:49], v[138:139]
	v_exp_f32_e32 v136, v136
	v_exp_f32_e32 v137, v137
	v_exp_f32_e32 v138, v138
	v_exp_f32_e32 v139, v139
	v_pk_add_f32 v[136:137], v[136:137], 1.0 op_sel_hi:[1,0]
	v_pk_add_f32 v[138:139], v[138:139], 1.0 op_sel_hi:[1,0]
	v_rcp_f32_e32 v136, v136
	v_rcp_f32_e32 v137, v137
	v_rcp_f32_e32 v138, v138
	v_rcp_f32_e32 v139, v139
	v_pk_mul_f32 v[46:47], v[46:47], v[136:137]
	v_pk_mul_f32 v[48:49], v[48:49], v[138:139]
	v_pk_mul_f32 v[136:137], v[42:43], v[42:43]
	v_pk_mul_f32 v[138:139], v[44:45], v[44:45]
	v_pk_fma_f32 v[136:137], v[136:137], v[144:145], v[146:147] op_sel_hi:[1,0,0]
	v_pk_fma_f32 v[138:139], v[138:139], v[144:145], v[146:147] op_sel_hi:[1,0,0]
	v_pk_mul_f32 v[136:137], v[42:43], v[136:137]
	v_pk_mul_f32 v[138:139], v[44:45], v[138:139]
	v_exp_f32_e32 v136, v136
	v_exp_f32_e32 v137, v137
	v_exp_f32_e32 v138, v138
	v_exp_f32_e32 v139, v139
	v_pk_add_f32 v[136:137], v[136:137], 1.0 op_sel_hi:[1,0]
	v_pk_add_f32 v[138:139], v[138:139], 1.0 op_sel_hi:[1,0]
	v_rcp_f32_e32 v136, v136
	v_rcp_f32_e32 v137, v137
	v_rcp_f32_e32 v138, v138
	v_rcp_f32_e32 v139, v139
	v_pk_mul_f32 v[42:43], v[42:43], v[136:137]
	v_pk_mul_f32 v[44:45], v[44:45], v[138:139]
	v_cvt_pk_bf16_f32 v46, v46, v47
	v_cvt_pk_bf16_f32 v47, v48, v49
	v_cvt_pk_bf16_f32 v48, v42, v43
	v_cvt_pk_bf16_f32 v49, v44, v45
	global_store_dwordx4 v134, v[46:49], s[0:1]
	v_pk_mul_f32 v[136:137], v[38:39], v[38:39]
	v_pk_mul_f32 v[138:139], v[40:41], v[40:41]
	v_pk_fma_f32 v[136:137], v[136:137], v[144:145], v[146:147] op_sel_hi:[1,0,0]
	v_pk_fma_f32 v[138:139], v[138:139], v[144:145], v[146:147] op_sel_hi:[1,0,0]
	v_pk_mul_f32 v[136:137], v[38:39], v[136:137]
	v_pk_mul_f32 v[138:139], v[40:41], v[138:139]
	v_exp_f32_e32 v136, v136
	v_exp_f32_e32 v137, v137
	v_exp_f32_e32 v138, v138
	v_exp_f32_e32 v139, v139
	v_pk_add_f32 v[136:137], v[136:137], 1.0 op_sel_hi:[1,0]
	v_pk_add_f32 v[138:139], v[138:139], 1.0 op_sel_hi:[1,0]
	v_rcp_f32_e32 v136, v136
	v_rcp_f32_e32 v137, v137
	v_rcp_f32_e32 v138, v138
	v_rcp_f32_e32 v139, v139
	v_pk_mul_f32 v[38:39], v[38:39], v[136:137]
	v_pk_mul_f32 v[40:41], v[40:41], v[138:139]
	v_pk_mul_f32 v[136:137], v[34:35], v[34:35]
	v_pk_mul_f32 v[138:139], v[36:37], v[36:37]
	v_pk_fma_f32 v[136:137], v[136:137], v[144:145], v[146:147] op_sel_hi:[1,0,0]
	v_pk_fma_f32 v[138:139], v[138:139], v[144:145], v[146:147] op_sel_hi:[1,0,0]
	v_pk_mul_f32 v[136:137], v[34:35], v[136:137]
	v_pk_mul_f32 v[138:139], v[36:37], v[138:139]
	v_exp_f32_e32 v136, v136
	v_exp_f32_e32 v137, v137
	v_exp_f32_e32 v138, v138
	v_exp_f32_e32 v139, v139
	v_pk_add_f32 v[136:137], v[136:137], 1.0 op_sel_hi:[1,0]
	v_pk_add_f32 v[138:139], v[138:139], 1.0 op_sel_hi:[1,0]
	v_rcp_f32_e32 v136, v136
	v_rcp_f32_e32 v137, v137
	v_rcp_f32_e32 v138, v138
	v_rcp_f32_e32 v139, v139
	v_pk_mul_f32 v[34:35], v[34:35], v[136:137]
	v_pk_mul_f32 v[36:37], v[36:37], v[138:139]
	v_cvt_pk_bf16_f32 v38, v38, v39
	v_cvt_pk_bf16_f32 v39, v40, v41
	v_cvt_pk_bf16_f32 v40, v34, v35
	v_cvt_pk_bf16_f32 v41, v36, v37
	global_store_dwordx4 v134, v[38:41], s[0:1] offset:256
	s_add_u32 s0, s0, 0x10000
	s_addc_u32 s1, s1, 0
	v_pk_mul_f32 v[136:137], v[30:31], v[30:31]
	v_pk_mul_f32 v[138:139], v[32:33], v[32:33]
	v_pk_fma_f32 v[136:137], v[136:137], v[144:145], v[146:147] op_sel_hi:[1,0,0]
	v_pk_fma_f32 v[138:139], v[138:139], v[144:145], v[146:147] op_sel_hi:[1,0,0]
	v_pk_mul_f32 v[136:137], v[30:31], v[136:137]
	v_pk_mul_f32 v[138:139], v[32:33], v[138:139]
	v_exp_f32_e32 v136, v136
	v_exp_f32_e32 v137, v137
	v_exp_f32_e32 v138, v138
	v_exp_f32_e32 v139, v139
	v_pk_add_f32 v[136:137], v[136:137], 1.0 op_sel_hi:[1,0]
	v_pk_add_f32 v[138:139], v[138:139], 1.0 op_sel_hi:[1,0]
	v_rcp_f32_e32 v136, v136
	v_rcp_f32_e32 v137, v137
	v_rcp_f32_e32 v138, v138
	v_rcp_f32_e32 v139, v139
	v_pk_mul_f32 v[30:31], v[30:31], v[136:137]
	v_pk_mul_f32 v[32:33], v[32:33], v[138:139]
	v_pk_mul_f32 v[136:137], v[26:27], v[26:27]
	v_pk_mul_f32 v[138:139], v[28:29], v[28:29]
	v_pk_fma_f32 v[136:137], v[136:137], v[144:145], v[146:147] op_sel_hi:[1,0,0]
	v_pk_fma_f32 v[138:139], v[138:139], v[144:145], v[146:147] op_sel_hi:[1,0,0]
	v_pk_mul_f32 v[136:137], v[26:27], v[136:137]
; __device__ __forceinline__ unsigned pk2(float lo, float hi) { f32x2 v = {lo, hi}; bf16x2_t b = __builtin_convertvector(v, bf16x2_t); return __builtin_bit_cast(unsigned, b); }
; __device__ __forceinline__ float gelu_tanh_(float v) { const float u = 1.5957691216057308f * (v + 0.044715f * v * v * v); return v * frcp_(1.0f + __expf(-u)); }
;     __device__ __forceinline__ void operator()(const AccT& acc, const Unit& u, int wr, int wc, int fr_in, int fq_in) const {
;     ...
;             for (int m = 0; m < 4; ++m) { bf16* rowp = base + (size_t)(row0 + ai * HALF + m * 16) * D + col0;
; #pragma unroll
;                 for (int bj = 0; bj < 2; ++bj) { f32x4 v0 = acc[ai][bj][m][0], v1 = acc[ai][bj][m][1];
;                     if (isg) {
; #pragma unroll
;                         for (int j = 0; j < 4; ++j) { v0[j] = gelu_tanh_(v0[j]); v1[j] = gelu_tanh_(v1[j]); } }
;                     u32x4 w; w.x = pk2(v0[0], v0[1]); w.y = pk2(v0[2], v0[3]); w.z = pk2(v1[0], v1[1]); w.w = pk2(v1[2], v1[3]);
;                     *(u32x4*)(rowp + bj * HALF) = w; } }
	v_pk_mul_f32 v[138:139], v[28:29], v[138:139]
	v_exp_f32_e32 v136, v136
	v_exp_f32_e32 v137, v137
	v_exp_f32_e32 v138, v138
	v_exp_f32_e32 v139, v139
	v_pk_add_f32 v[136:137], v[136:137], 1.0 op_sel_hi:[1,0]
	v_pk_add_f32 v[138:139], v[138:139], 1.0 op_sel_hi:[1,0]
	v_rcp_f32_e32 v136, v136
	v_rcp_f32_e32 v137, v137
	v_rcp_f32_e32 v138, v138
	v_rcp_f32_e32 v139, v139
	v_pk_mul_f32 v[26:27], v[26:27], v[136:137]
	v_pk_mul_f32 v[28:29], v[28:29], v[138:139]
	v_cvt_pk_bf16_f32 v30, v30, v31
	v_cvt_pk_bf16_f32 v31, v32, v33
	v_cvt_pk_bf16_f32 v32, v26, v27
	v_cvt_pk_bf16_f32 v33, v28, v29
	global_store_dwordx4 v134, v[30:33], s[0:1]
	v_pk_mul_f32 v[136:137], v[22:23], v[22:23]
	v_pk_mul_f32 v[138:139], v[24:25], v[24:25]
	v_pk_fma_f32 v[136:137], v[136:137], v[144:145], v[146:147] op_sel_hi:[1,0,0]
	v_pk_fma_f32 v[138:139], v[138:139], v[144:145], v[146:147] op_sel_hi:[1,0,0]
	v_pk_mul_f32 v[136:137], v[22:23], v[136:137]
	v_pk_mul_f32 v[138:139], v[24:25], v[138:139]
	v_exp_f32_e32 v136, v136
	v_exp_f32_e32 v137, v137
	v_exp_f32_e32 v138, v138
	v_exp_f32_e32 v139, v139
	v_pk_add_f32 v[136:137], v[136:137], 1.0 op_sel_hi:[1,0]
	v_pk_add_f32 v[138:139], v[138:139], 1.0 op_sel_hi:[1,0]
	v_rcp_f32_e32 v136, v136
	v_rcp_f32_e32 v137, v137
	v_rcp_f32_e32 v138, v138
	v_rcp_f32_e32 v139, v139
	v_pk_mul_f32 v[22:23], v[22:23], v[136:137]
	v_pk_mul_f32 v[24:25], v[24:25], v[138:139]
	v_pk_mul_f32 v[136:137], v[18:19], v[18:19]
	v_pk_mul_f32 v[138:139], v[20:21], v[20:21]
	v_pk_fma_f32 v[136:137], v[136:137], v[144:145], v[146:147] op_sel_hi:[1,0,0]
	v_pk_fma_f32 v[138:139], v[138:139], v[144:145], v[146:147] op_sel_hi:[1,0,0]
	v_pk_mul_f32 v[136:137], v[18:19], v[136:137]
	v_pk_mul_f32 v[138:139], v[20:21], v[138:139]
	v_exp_f32_e32 v136, v136
	v_exp_f32_e32 v137, v137
	v_exp_f32_e32 v138, v138
	v_exp_f32_e32 v139, v139
	v_pk_add_f32 v[136:137], v[136:137], 1.0 op_sel_hi:[1,0]
	v_pk_add_f32 v[138:139], v[138:139], 1.0 op_sel_hi:[1,0]
	v_rcp_f32_e32 v136, v136
	v_rcp_f32_e32 v137, v137
	v_rcp_f32_e32 v138, v138
	v_rcp_f32_e32 v139, v139
	v_pk_mul_f32 v[18:19], v[18:19], v[136:137]
	v_pk_mul_f32 v[20:21], v[20:21], v[138:139]
	v_cvt_pk_bf16_f32 v22, v22, v23
	v_cvt_pk_bf16_f32 v23, v24, v25
	v_cvt_pk_bf16_f32 v24, v18, v19
	v_cvt_pk_bf16_f32 v25, v20, v21
	global_store_dwordx4 v134, v[22:25], s[0:1] offset:256
	s_add_u32 s0, s0, 0x10000
	s_addc_u32 s1, s1, 0
	v_pk_mul_f32 v[136:137], v[14:15], v[14:15]
	v_pk_mul_f32 v[138:139], v[16:17], v[16:17]
	v_pk_fma_f32 v[136:137], v[136:137], v[144:145], v[146:147] op_sel_hi:[1,0,0]
	v_pk_fma_f32 v[138:139], v[138:139], v[144:145], v[146:147] op_sel_hi:[1,0,0]
	v_pk_mul_f32 v[136:137], v[14:15], v[136:137]
	v_pk_mul_f32 v[138:139], v[16:17], v[138:139]
	v_exp_f32_e32 v136, v136
	v_exp_f32_e32 v137, v137
	v_exp_f32_e32 v138, v138
	v_exp_f32_e32 v139, v139
	v_pk_add_f32 v[136:137], v[136:137], 1.0 op_sel_hi:[1,0]
	v_pk_add_f32 v[138:139], v[138:139], 1.0 op_sel_hi:[1,0]
	v_rcp_f32_e32 v136, v136
	v_rcp_f32_e32 v137, v137
	v_rcp_f32_e32 v138, v138
	v_rcp_f32_e32 v139, v139
	v_pk_mul_f32 v[14:15], v[14:15], v[136:137]
	v_pk_mul_f32 v[16:17], v[16:17], v[138:139]
	v_pk_mul_f32 v[136:137], v[10:11], v[10:11]
	v_pk_mul_f32 v[138:139], v[12:13], v[12:13]
	v_pk_fma_f32 v[136:137], v[136:137], v[144:145], v[146:147] op_sel_hi:[1,0,0]
	v_pk_fma_f32 v[138:139], v[138:139], v[144:145], v[146:147] op_sel_hi:[1,0,0]
	v_pk_mul_f32 v[136:137], v[10:11], v[136:137]
	v_pk_mul_f32 v[138:139], v[12:13], v[138:139]
	v_exp_f32_e32 v136, v136
	v_exp_f32_e32 v137, v137
	v_exp_f32_e32 v138, v138
	v_exp_f32_e32 v139, v139
	v_pk_add_f32 v[136:137], v[136:137], 1.0 op_sel_hi:[1,0]
	v_pk_add_f32 v[138:139], v[138:139], 1.0 op_sel_hi:[1,0]
	v_rcp_f32_e32 v136, v136
	v_rcp_f32_e32 v137, v137
	v_rcp_f32_e32 v138, v138
	v_rcp_f32_e32 v139, v139
	v_pk_mul_f32 v[10:11], v[10:11], v[136:137]
	v_pk_mul_f32 v[12:13], v[12:13], v[138:139]
	v_cvt_pk_bf16_f32 v14, v14, v15
	v_cvt_pk_bf16_f32 v15, v16, v17
	v_cvt_pk_bf16_f32 v16, v10, v11
	v_cvt_pk_bf16_f32 v17, v12, v13
	global_store_dwordx4 v134, v[14:17], s[0:1]
	v_pk_mul_f32 v[136:137], v[6:7], v[6:7]
	v_pk_mul_f32 v[138:139], v[8:9], v[8:9]
	v_pk_fma_f32 v[136:137], v[136:137], v[144:145], v[146:147] op_sel_hi:[1,0,0]
	v_pk_fma_f32 v[138:139], v[138:139], v[144:145], v[146:147] op_sel_hi:[1,0,0]
	v_pk_mul_f32 v[136:137], v[6:7], v[136:137]
	v_pk_mul_f32 v[138:139], v[8:9], v[138:139]
	v_exp_f32_e32 v136, v136
	v_exp_f32_e32 v137, v137
	v_exp_f32_e32 v138, v138
	v_exp_f32_e32 v139, v139
	v_pk_add_f32 v[136:137], v[136:137], 1.0 op_sel_hi:[1,0]
	v_pk_add_f32 v[138:139], v[138:139], 1.0 op_sel_hi:[1,0]
	v_rcp_f32_e32 v136, v136
	v_rcp_f32_e32 v137, v137
	v_rcp_f32_e32 v138, v138
	v_rcp_f32_e32 v139, v139
	v_pk_mul_f32 v[6:7], v[6:7], v[136:137]
	v_pk_mul_f32 v[8:9], v[8:9], v[138:139]
	v_pk_mul_f32 v[136:137], v[2:3], v[2:3]
	v_pk_mul_f32 v[138:139], v[4:5], v[4:5]
	v_pk_fma_f32 v[136:137], v[136:137], v[144:145], v[146:147] op_sel_hi:[1,0,0]
	v_pk_fma_f32 v[138:139], v[138:139], v[144:145], v[146:147] op_sel_hi:[1,0,0]
	v_pk_mul_f32 v[136:137], v[2:3], v[136:137]
	v_pk_mul_f32 v[138:139], v[4:5], v[138:139]
	v_exp_f32_e32 v136, v136
	v_exp_f32_e32 v137, v137
	v_exp_f32_e32 v138, v138
	v_exp_f32_e32 v139, v139
	v_pk_add_f32 v[136:137], v[136:137], 1.0 op_sel_hi:[1,0]
	v_pk_add_f32 v[138:139], v[138:139], 1.0 op_sel_hi:[1,0]
	v_rcp_f32_e32 v136, v136
	v_rcp_f32_e32 v137, v137
	v_rcp_f32_e32 v138, v138
	v_rcp_f32_e32 v139, v139
	v_pk_mul_f32 v[2:3], v[2:3], v[136:137]
	v_pk_mul_f32 v[4:5], v[4:5], v[138:139]
	v_cvt_pk_bf16_f32 v6, v6, v7
	v_cvt_pk_bf16_f32 v7, v8, v9
	v_cvt_pk_bf16_f32 v8, v2, v3
	v_cvt_pk_bf16_f32 v9, v4, v5
	global_store_dwordx4 v134, v[6:9], s[0:1] offset:256
	s_branch .Lrgepi_done
; __device__ __forceinline__ unsigned pk2(float lo, float hi) { f32x2 v = {lo, hi}; bf16x2_t b = __builtin_convertvector(v, bf16x2_t); return __builtin_bit_cast(unsigned, b); }
; __device__ __forceinline__ float gelu_tanh_(float v) { const float u = 1.5957691216057308f * (v + 0.044715f * v * v * v); return v * frcp_(1.0f + __expf(-u)); }
;     __device__ __forceinline__ void operator()(const AccT& acc, const Unit& u, int wr, int wc, int fr_in, int fq_in) const {
;     ...
;             for (int m = 0; m < 4; ++m) { bf16* rowp = base + (size_t)(row0 + ai * HALF + m * 16) * D + col0;
; #pragma unroll
;                 for (int bj = 0; bj < 2; ++bj) { f32x4 v0 = acc[ai][bj][m][0], v1 = acc[ai][bj][m][1];
;                     if (isg) {
; #pragma unroll
;                         for (int j = 0; j < 4; ++j) { v0[j] = gelu_tanh_(v0[j]); v1[j] = gelu_tanh_(v1[j]); } }
;                     u32x4 w; w.x = pk2(v0[0], v0[1]); w.y = pk2(v0[2], v0[3]); w.z = pk2(v1[0], v1[1]); w.w = pk2(v1[2], v1[3]);
;                     *(u32x4*)(rowp + bj * HALF) = w; } }
.Lrgepi_raw:
	v_cvt_pk_bf16_f32 v126, v126, v127
	v_cvt_pk_bf16_f32 v127, v128, v129
	v_cvt_pk_bf16_f32 v128, v122, v123
	v_cvt_pk_bf16_f32 v129, v124, v125
	global_store_dwordx4 v134, v[126:129], s[0:1]
	v_cvt_pk_bf16_f32 v118, v118, v119
	v_cvt_pk_bf16_f32 v119, v120, v121
	v_cvt_pk_bf16_f32 v120, v114, v115
	v_cvt_pk_bf16_f32 v121, v116, v117
	global_store_dwordx4 v134, v[118:121], s[0:1] offset:256
	s_add_u32 s0, s0, 0x10000
	s_addc_u32 s1, s1, 0
	v_cvt_pk_bf16_f32 v110, v110, v111
	v_cvt_pk_bf16_f32 v111, v112, v113
	v_cvt_pk_bf16_f32 v112, v106, v107
	v_cvt_pk_bf16_f32 v113, v108, v109
	global_store_dwordx4 v134, v[110:113], s[0:1]
	v_cvt_pk_bf16_f32 v102, v102, v103
	v_cvt_pk_bf16_f32 v103, v104, v105
	v_cvt_pk_bf16_f32 v104, v98, v99
	v_cvt_pk_bf16_f32 v105, v100, v101
	global_store_dwordx4 v134, v[102:105], s[0:1] offset:256
	s_add_u32 s0, s0, 0x10000
	s_addc_u32 s1, s1, 0
	v_cvt_pk_bf16_f32 v94, v94, v95
	v_cvt_pk_bf16_f32 v95, v96, v97
	v_cvt_pk_bf16_f32 v96, v90, v91
	v_cvt_pk_bf16_f32 v97, v92, v93
	global_store_dwordx4 v134, v[94:97], s[0:1]
	v_cvt_pk_bf16_f32 v86, v86, v87
	v_cvt_pk_bf16_f32 v87, v88, v89
	v_cvt_pk_bf16_f32 v88, v82, v83
	v_cvt_pk_bf16_f32 v89, v84, v85
	global_store_dwordx4 v134, v[86:89], s[0:1] offset:256
	s_add_u32 s0, s0, 0x10000
	s_addc_u32 s1, s1, 0
	v_cvt_pk_bf16_f32 v78, v78, v79
	v_cvt_pk_bf16_f32 v79, v80, v81
	v_cvt_pk_bf16_f32 v80, v74, v75
	v_cvt_pk_bf16_f32 v81, v76, v77
	global_store_dwordx4 v134, v[78:81], s[0:1]
	v_cvt_pk_bf16_f32 v70, v70, v71
	v_cvt_pk_bf16_f32 v71, v72, v73
	v_cvt_pk_bf16_f32 v72, v66, v67
	v_cvt_pk_bf16_f32 v73, v68, v69
	global_store_dwordx4 v134, v[70:73], s[0:1] offset:256
	s_add_u32 s0, s0, 0x50000
	s_addc_u32 s1, s1, 0
	v_cvt_pk_bf16_f32 v62, v62, v63
	v_cvt_pk_bf16_f32 v63, v64, v65
	v_cvt_pk_bf16_f32 v64, v58, v59
	v_cvt_pk_bf16_f32 v65, v60, v61
	global_store_dwordx4 v134, v[62:65], s[0:1]
	v_cvt_pk_bf16_f32 v54, v54, v55
	v_cvt_pk_bf16_f32 v55, v56, v57
	v_cvt_pk_bf16_f32 v56, v50, v51
	v_cvt_pk_bf16_f32 v57, v52, v53
	global_store_dwordx4 v134, v[54:57], s[0:1] offset:256
	s_add_u32 s0, s0, 0x10000
	s_addc_u32 s1, s1, 0
	v_cvt_pk_bf16_f32 v46, v46, v47
	v_cvt_pk_bf16_f32 v47, v48, v49
	v_cvt_pk_bf16_f32 v48, v42, v43
	v_cvt_pk_bf16_f32 v49, v44, v45
	global_store_dwordx4 v134, v[46:49], s[0:1]
	v_cvt_pk_bf16_f32 v38, v38, v39
	v_cvt_pk_bf16_f32 v39, v40, v41
	v_cvt_pk_bf16_f32 v40, v34, v35
	v_cvt_pk_bf16_f32 v41, v36, v37
	global_store_dwordx4 v134, v[38:41], s[0:1] offset:256
	s_add_u32 s0, s0, 0x10000
	s_addc_u32 s1, s1, 0
	v_cvt_pk_bf16_f32 v30, v30, v31
	v_cvt_pk_bf16_f32 v31, v32, v33
	v_cvt_pk_bf16_f32 v32, v26, v27
	v_cvt_pk_bf16_f32 v33, v28, v29
	global_store_dwordx4 v134, v[30:33], s[0:1]
	v_cvt_pk_bf16_f32 v22, v22, v23
	v_cvt_pk_bf16_f32 v23, v24, v25
	v_cvt_pk_bf16_f32 v24, v18, v19
	v_cvt_pk_bf16_f32 v25, v20, v21
	global_store_dwordx4 v134, v[22:25], s[0:1] offset:256
	s_add_u32 s0, s0, 0x10000
	s_addc_u32 s1, s1, 0
	v_cvt_pk_bf16_f32 v14, v14, v15
	v_cvt_pk_bf16_f32 v15, v16, v17
	v_cvt_pk_bf16_f32 v16, v10, v11
	v_cvt_pk_bf16_f32 v17, v12, v13
	global_store_dwordx4 v134, v[14:17], s[0:1]
	v_cvt_pk_bf16_f32 v6, v6, v7
	v_cvt_pk_bf16_f32 v7, v8, v9
	v_cvt_pk_bf16_f32 v8, v2, v3
	v_cvt_pk_bf16_f32 v9, v4, v5
	global_store_dwordx4 v134, v[6:9], s[0:1] offset:256
.Lrgepi_done:
	s_andn2_b64 vcc, exec, s[38:39]
	s_mov_b64 s[22:23], -1
	s_cbranch_vccnz .LBB0_731
	s_andn2_b64 vcc, exec, s[16:17]
	s_cbranch_vccnz .LBB0_730
	s_barrier
	s_branch .LBB0_730
